# strategy 4, per-half comparison: the static s_setprio 1 given to waves 0-3 instead of waves 4-7 (otherwise v023)
# baseline (speedup 1.0000x reference)
; template <int LO, int HI> __global__ void __launch_bounds__(NTHR, 2) mega(P p) {
;     ...
;         scan_prep(p, F);
;         if (F.bid < NSEQ_P * 32) {
;             CKIN_DECL(i); CKIN_LOAD(i, F.bid); int ptag0 = -1, ptag1 = -1;
;             __syncthreads();
;             for (int task = F.bid; task < NSEQ_P * 32; task += F.G) chunk_pre(p, F, task, task + F.G < NSEQ_P * 32 ? task + F.G : task, icr, ick, icv, ipr, ipk, ipv, ia0, ia1, iw0, iw1, ptag0, ptag1); }
.LBB0_1613:
	v_readfirstlane_b32 s6, v0
	s_nop 3
	s_bitcmp1_b32 s6, 8
	s_cbranch_scc1 .Lprio_p7_done
	s_setprio 1

; template <int LO, int HI> __global__ void __launch_bounds__(NTHR, 2) mega(P p) {
;     ...
; #pragma nounroll
;           for (;;) {
;               if (F.tid == 0) MISC[0] = __hip_atomic_fetch_add(qctr, 1u, __ATOMIC_RELAXED, __HIP_MEMORY_SCOPE_AGENT);
;               __syncthreads();
;               const int k = (int)MISC[0];
;               __syncthreads();
;               constexpr int NATT = 576, NCONV = (TR_NLATE + 15) / 16;
;               if (k >= NATT + NCONV) break;
;               int ia = -1, ic = -1;
;               if (k < 2 * NATT) { if (k & 1) ic = k >> 1; else ia = k >> 1; } else ic = k - NATT;
;               if (ic >= 0) { tr_late_batch(p, F, ic); continue; }
;               const bool is_s = ia < 64; const int kk = is_s ? ia : ia - 64;
;               attn_item(p, F, is_s, is_s ? kk >> 1 : (kk & 15) >> 1, kk & 1, is_s ? 0 : 31 - (kk >> 4)); } }
.LBB0_1864:
	v_readfirstlane_b32 s0, v0
	s_nop 3
	s_bitcmp1_b32 s0, 8
	s_cbranch_scc1 .Lprio_p8_done
	s_setprio 1
